# RWKV consumer: next-step kk/k/v LDS loads issued at step start (full step of latency budget)
# baseline (speedup 1.0000x reference)
; __device__ __forceinline__ float afma(float a, float b, float c) { float d; asm("v_fma_f32 %0, %1, %2, %3" : "=v"(d) : "v"(a), "v"(b), "v"(c)); return d; }
; __device__ __forceinline__ float amul(float a, float b) { float d; asm("v_mul_f32 %0, %1, %2" : "=v"(d) : "v"(a), "v"(b)); return d; }
; __device__ __forceinline__ void phase_scans(const Params& p, unsigned char* lds) {
;     ...
;                 const float* bufp = sRW + (ci & 1) * 6656;
;                 const float* sO = bufp + 4 * ksl; const float* sV = bufp + 5120 + 32 * rh + rowl;
;                 float* ydst = (ksl == 0) ? ((float*)bufp + 6144 + rowl) : (sRW + 13312 + ct);
;                 const int ystep = (ksl == 0) ? 32 : 0;
;     ...
;                 f32x4 r4[2], w4[2], k4[2], kk4[2], na4[2]; float v1;
;                 RW_OPS(0, r4, w4, k4, kk4, na4, v1);
; #pragma unroll 2
;                 for (int s = 0; s < 16; ++s) {
;                     const int sn = (s + 1) & 15;
;                     f32x4 r4n[2], w4n[2], k4n[2], kk4n[2], na4n[2]; float v1n;
;                     RW_OPS(sn, r4n, w4n, k4n, kk4n, na4n, v1n);
;                     float d0 = amul(S[0], kk4[0][0]), d1 = amul(S[4], kk4[1][0]);
; #pragma unroll
;                     for (int j = 1; j < 4; ++j) { d0 = afma(S[j], kk4[0][j], d0); d1 = afma(S[4 + j], kk4[1][j], d1); }
;                     const float d = dpp_sum8(d0 + d1);
; #pragma unroll
;                     for (int j = 0; j < 4; ++j) {
;                         S[j] = afma(v1, k4[0][j], afma(S[j], w4[0][j], amul(d, na4[0][j])));
;                         S[4 + j] = afma(v1, k4[1][j], afma(S[4 + j], w4[1][j], amul(d, na4[1][j]))); }
;                     float y0 = amul(S[0], r4[0][0]), y1 = amul(S[4], r4[1][0]);
; #pragma unroll
;                     for (int j = 1; j < 4; ++j) { y0 = afma(S[j], r4[0][j], y0); y1 = afma(S[4 + j], r4[1][j], y1); }
;                     const float y = dpp_sum8(y0 + y1);
;                     ydst[s * ystep] = y;
.Lrw_chunk:
	s_bitcmp1_b32 s4, 0
	s_cselect_b32 s6, 0x6800, 0
	v_add_u32_e32 v113, s6, v99
	v_add_u32_e32 v114, s6, v101
	v_add_u32_e32 v115, s6, v110
	ds_read_b128 v[18:21], v113 offset:12288
	ds_read_b128 v[22:25], v113 offset:12416
	ds_read_b128 v[26:29], v113 offset:8192
	ds_read_b128 v[30:33], v113 offset:8320
	ds_read_b32 v98, v114 offset:20480
	ds_read_b128 v[34:37], v113 offset:4096
	ds_read_b128 v[38:41], v113 offset:4224
	ds_read_b128 v[42:45], v113 offset:16384
	ds_read_b128 v[46:49], v113 offset:16512
	ds_read_b128 v[50:53], v113 offset:0
	ds_read_b128 v[54:57], v113 offset:128
	v_cndmask_b32_e32 v115, v111, v115, vcc
	s_waitcnt lgkmcnt(9)
	ds_read_b128 v[58:61], v113 offset:12544
	ds_read_b128 v[62:65], v113 offset:12672
	ds_read_b128 v[66:69], v113 offset:8448
	ds_read_b128 v[70:73], v113 offset:8576
	ds_read_b32 v100, v114 offset:20736
	v_pk_mul_f32 v[18:19], v[102:103], v[18:19]
	v_pk_fma_f32 v[18:19], v[104:105], v[20:21], v[18:19]
	v_pk_fma_f32 v[18:19], v[106:107], v[22:23], v[18:19]
	v_pk_fma_f32 v[18:19], v[108:109], v[24:25], v[18:19]
	v_add_f32_e32 v18, v18, v19
	s_waitcnt lgkmcnt(11)
	v_pk_mul_f32 v[26:27], v[26:27], v[98:99] op_sel_hi:[1,0]
	v_pk_mul_f32 v[28:29], v[28:29], v[98:99] op_sel_hi:[1,0]
	v_add_f32_dpp v18, v18, v18 quad_perm:[1,0,3,2] row_mask:0xf bank_mask:0xf bound_ctrl:1
	v_pk_mul_f32 v[30:31], v[30:31], v[98:99] op_sel_hi:[1,0]
	v_pk_mul_f32 v[32:33], v[32:33], v[98:99] op_sel_hi:[1,0]
	s_waitcnt lgkmcnt(9)
	ds_read_b128 v[74:77], v113 offset:4352
	ds_read_b128 v[78:81], v113 offset:4480
	ds_read_b128 v[82:85], v113 offset:16640
	ds_read_b128 v[86:89], v113 offset:16768
	ds_read_b128 v[90:93], v113 offset:256
	ds_read_b128 v[94:97], v113 offset:384
	v_pk_fma_f32 v[26:27], v[102:103], v[34:35], v[26:27]
	v_add_f32_dpp v18, v18, v18 quad_perm:[2,3,0,1] row_mask:0xf bank_mask:0xf bound_ctrl:1
	v_pk_fma_f32 v[28:29], v[104:105], v[36:37], v[28:29]
	v_pk_fma_f32 v[30:31], v[106:107], v[38:39], v[30:31]
	v_add_f32_dpp v18, v18, v18 row_half_mirror row_mask:0xf bank_mask:0xf bound_ctrl:1
	v_pk_fma_f32 v[32:33], v[108:109], v[40:41], v[32:33]
	s_nop 0
	s_waitcnt lgkmcnt(13)
	v_pk_fma_f32 v[102:103], v[18:19], v[42:43], v[26:27] op_sel_hi:[0,1,1]
	v_pk_fma_f32 v[104:105], v[18:19], v[44:45], v[28:29] op_sel_hi:[0,1,1]
	v_pk_fma_f32 v[106:107], v[18:19], v[46:47], v[30:31] op_sel_hi:[0,1,1]
	v_pk_fma_f32 v[108:109], v[18:19], v[48:49], v[32:33] op_sel_hi:[0,1,1]
	s_waitcnt lgkmcnt(9)
	ds_read_b128 v[18:21], v113 offset:12800
	ds_read_b128 v[22:25], v113 offset:12928
	ds_read_b128 v[26:29], v113 offset:8704
	ds_read_b128 v[30:33], v113 offset:8832
	ds_read_b32 v98, v114 offset:20992
	v_pk_mul_f32 v[58:59], v[102:103], v[58:59]
	v_pk_mul_f32 v[50:51], v[102:103], v[50:51]
	v_pk_fma_f32 v[58:59], v[104:105], v[60:61], v[58:59]
	v_pk_fma_f32 v[50:51], v[104:105], v[52:53], v[50:51]
	v_pk_fma_f32 v[58:59], v[106:107], v[62:63], v[58:59]
	v_pk_fma_f32 v[50:51], v[106:107], v[54:55], v[50:51]
	v_pk_fma_f32 v[58:59], v[108:109], v[64:65], v[58:59]
	v_pk_fma_f32 v[50:51], v[108:109], v[56:57], v[50:51]
	v_add_f32_e32 v58, v58, v59
	v_add_f32_e32 v50, v50, v51
	s_waitcnt lgkmcnt(11)
	v_pk_mul_f32 v[66:67], v[66:67], v[100:101] op_sel_hi:[1,0]
	v_add_f32_dpp v58, v58, v58 quad_perm:[1,0,3,2] row_mask:0xf bank_mask:0xf bound_ctrl:1
	v_add_f32_dpp v50, v50, v50 quad_perm:[1,0,3,2] row_mask:0xf bank_mask:0xf bound_ctrl:1
	v_pk_mul_f32 v[68:69], v[68:69], v[100:101] op_sel_hi:[1,0]
	v_add_f32_dpp v58, v58, v58 quad_perm:[2,3,0,1] row_mask:0xf bank_mask:0xf bound_ctrl:1
	v_add_f32_dpp v50, v50, v50 quad_perm:[2,3,0,1] row_mask:0xf bank_mask:0xf bound_ctrl:1
	v_pk_mul_f32 v[70:71], v[70:71], v[100:101] op_sel_hi:[1,0]
	v_add_f32_dpp v58, v58, v58 row_half_mirror row_mask:0xf bank_mask:0xf bound_ctrl:1
	v_add_f32_dpp v50, v50, v50 row_half_mirror row_mask:0xf bank_mask:0xf bound_ctrl:1
	v_pk_mul_f32 v[72:73], v[72:73], v[100:101] op_sel_hi:[1,0]
	ds_write_b32 v115, v50
	v_add_u32_e32 v115, v115, v112
	s_waitcnt lgkmcnt(9)
	ds_read_b128 v[34:37], v113 offset:4608
	ds_read_b128 v[38:41], v113 offset:4736
	ds_read_b128 v[42:45], v113 offset:16896
	ds_read_b128 v[46:49], v113 offset:17024
	ds_read_b128 v[50:53], v113 offset:512
	ds_read_b128 v[54:57], v113 offset:640
	v_pk_fma_f32 v[66:67], v[102:103], v[74:75], v[66:67]
	v_pk_fma_f32 v[68:69], v[104:105], v[76:77], v[68:69]
	v_pk_fma_f32 v[70:71], v[106:107], v[78:79], v[70:71]
	v_pk_fma_f32 v[72:73], v[108:109], v[80:81], v[72:73]
	s_waitcnt lgkmcnt(14)
	v_pk_fma_f32 v[102:103], v[58:59], v[82:83], v[66:67] op_sel_hi:[0,1,1]
	v_pk_fma_f32 v[104:105], v[58:59], v[84:85], v[68:69] op_sel_hi:[0,1,1]
	v_pk_fma_f32 v[106:107], v[58:59], v[86:87], v[70:71] op_sel_hi:[0,1,1]
	v_pk_fma_f32 v[108:109], v[58:59], v[88:89], v[72:73] op_sel_hi:[0,1,1]
	s_waitcnt lgkmcnt(10)
	ds_read_b128 v[58:61], v113 offset:13056
	ds_read_b128 v[62:65], v113 offset:13184
	ds_read_b128 v[66:69], v113 offset:8960
	ds_read_b128 v[70:73], v113 offset:9088
	ds_read_b32 v100, v114 offset:21248
	v_pk_mul_f32 v[18:19], v[102:103], v[18:19]
	v_pk_mul_f32 v[90:91], v[102:103], v[90:91]
	v_pk_fma_f32 v[18:19], v[104:105], v[20:21], v[18:19]
	v_pk_fma_f32 v[90:91], v[104:105], v[92:93], v[90:91]
	v_pk_fma_f32 v[18:19], v[106:107], v[22:23], v[18:19]
	v_pk_fma_f32 v[90:91], v[106:107], v[94:95], v[90:91]
	v_pk_fma_f32 v[18:19], v[108:109], v[24:25], v[18:19]
	v_pk_fma_f32 v[90:91], v[108:109], v[96:97], v[90:91]
	v_add_f32_e32 v18, v18, v19
	v_add_f32_e32 v90, v90, v91
	s_waitcnt lgkmcnt(12)
; __device__ __forceinline__ float afma(float a, float b, float c) { float d; asm("v_fma_f32 %0, %1, %2, %3" : "=v"(d) : "v"(a), "v"(b), "v"(c)); return d; }
; __device__ __forceinline__ float amul(float a, float b) { float d; asm("v_mul_f32 %0, %1, %2" : "=v"(d) : "v"(a), "v"(b)); return d; }
; __device__ __forceinline__ void phase_scans(const Params& p, unsigned char* lds) {
;     ...
;                 for (int s = 0; s < 16; ++s) {
;                     const int sn = (s + 1) & 15;
;                     f32x4 r4n[2], w4n[2], k4n[2], kk4n[2], na4n[2]; float v1n;
;                     RW_OPS(sn, r4n, w4n, k4n, kk4n, na4n, v1n);
;                     float d0 = amul(S[0], kk4[0][0]), d1 = amul(S[4], kk4[1][0]);
; #pragma unroll
;                     for (int j = 1; j < 4; ++j) { d0 = afma(S[j], kk4[0][j], d0); d1 = afma(S[4 + j], kk4[1][j], d1); }
;                     const float d = dpp_sum8(d0 + d1);
; #pragma unroll
;                     for (int j = 0; j < 4; ++j) {
;                         S[j] = afma(v1, k4[0][j], afma(S[j], w4[0][j], amul(d, na4[0][j])));
;                         S[4 + j] = afma(v1, k4[1][j], afma(S[4 + j], w4[1][j], amul(d, na4[1][j]))); }
;                     float y0 = amul(S[0], r4[0][0]), y1 = amul(S[4], r4[1][0]);
; #pragma unroll
;                     for (int j = 1; j < 4; ++j) { y0 = afma(S[j], r4[0][j], y0); y1 = afma(S[4 + j], r4[1][j], y1); }
;                     const float y = dpp_sum8(y0 + y1);
;                     ydst[s * ystep] = y;
	v_pk_mul_f32 v[26:27], v[26:27], v[98:99] op_sel_hi:[1,0]
	v_add_f32_dpp v18, v18, v18 quad_perm:[1,0,3,2] row_mask:0xf bank_mask:0xf bound_ctrl:1
	v_add_f32_dpp v90, v90, v90 quad_perm:[1,0,3,2] row_mask:0xf bank_mask:0xf bound_ctrl:1
	v_pk_mul_f32 v[28:29], v[28:29], v[98:99] op_sel_hi:[1,0]
	v_add_f32_dpp v18, v18, v18 quad_perm:[2,3,0,1] row_mask:0xf bank_mask:0xf bound_ctrl:1
	v_add_f32_dpp v90, v90, v90 quad_perm:[2,3,0,1] row_mask:0xf bank_mask:0xf bound_ctrl:1
	v_pk_mul_f32 v[30:31], v[30:31], v[98:99] op_sel_hi:[1,0]
	v_add_f32_dpp v18, v18, v18 row_half_mirror row_mask:0xf bank_mask:0xf bound_ctrl:1
	v_add_f32_dpp v90, v90, v90 row_half_mirror row_mask:0xf bank_mask:0xf bound_ctrl:1
	v_pk_mul_f32 v[32:33], v[32:33], v[98:99] op_sel_hi:[1,0]
	ds_write_b32 v115, v90
	v_add_u32_e32 v115, v115, v112
	s_waitcnt lgkmcnt(9)
	ds_read_b128 v[74:77], v113 offset:4864
	ds_read_b128 v[78:81], v113 offset:4992
	ds_read_b128 v[82:85], v113 offset:17152
	ds_read_b128 v[86:89], v113 offset:17280
	ds_read_b128 v[90:93], v113 offset:768
	ds_read_b128 v[94:97], v113 offset:896
	v_pk_fma_f32 v[26:27], v[102:103], v[34:35], v[26:27]
	v_pk_fma_f32 v[28:29], v[104:105], v[36:37], v[28:29]
	v_pk_fma_f32 v[30:31], v[106:107], v[38:39], v[30:31]
	v_pk_fma_f32 v[32:33], v[108:109], v[40:41], v[32:33]
	s_waitcnt lgkmcnt(14)
	v_pk_fma_f32 v[102:103], v[18:19], v[42:43], v[26:27] op_sel_hi:[0,1,1]
	v_pk_fma_f32 v[104:105], v[18:19], v[44:45], v[28:29] op_sel_hi:[0,1,1]
	v_pk_fma_f32 v[106:107], v[18:19], v[46:47], v[30:31] op_sel_hi:[0,1,1]
	v_pk_fma_f32 v[108:109], v[18:19], v[48:49], v[32:33] op_sel_hi:[0,1,1]
	s_waitcnt lgkmcnt(10)
	ds_read_b128 v[18:21], v113 offset:13312
	ds_read_b128 v[22:25], v113 offset:13440
	ds_read_b128 v[26:29], v113 offset:9216
	ds_read_b128 v[30:33], v113 offset:9344
	ds_read_b32 v98, v114 offset:21504
	v_pk_mul_f32 v[58:59], v[102:103], v[58:59]
	v_pk_mul_f32 v[50:51], v[102:103], v[50:51]
	v_pk_fma_f32 v[58:59], v[104:105], v[60:61], v[58:59]
	v_pk_fma_f32 v[50:51], v[104:105], v[52:53], v[50:51]
	v_pk_fma_f32 v[58:59], v[106:107], v[62:63], v[58:59]
	v_pk_fma_f32 v[50:51], v[106:107], v[54:55], v[50:51]
	v_pk_fma_f32 v[58:59], v[108:109], v[64:65], v[58:59]
	v_pk_fma_f32 v[50:51], v[108:109], v[56:57], v[50:51]
	v_add_f32_e32 v58, v58, v59
	v_add_f32_e32 v50, v50, v51
	s_waitcnt lgkmcnt(12)
	v_pk_mul_f32 v[66:67], v[66:67], v[100:101] op_sel_hi:[1,0]
	v_add_f32_dpp v58, v58, v58 quad_perm:[1,0,3,2] row_mask:0xf bank_mask:0xf bound_ctrl:1
	v_add_f32_dpp v50, v50, v50 quad_perm:[1,0,3,2] row_mask:0xf bank_mask:0xf bound_ctrl:1
	v_pk_mul_f32 v[68:69], v[68:69], v[100:101] op_sel_hi:[1,0]
	v_add_f32_dpp v58, v58, v58 quad_perm:[2,3,0,1] row_mask:0xf bank_mask:0xf bound_ctrl:1
	v_add_f32_dpp v50, v50, v50 quad_perm:[2,3,0,1] row_mask:0xf bank_mask:0xf bound_ctrl:1
	v_pk_mul_f32 v[70:71], v[70:71], v[100:101] op_sel_hi:[1,0]
	v_add_f32_dpp v58, v58, v58 row_half_mirror row_mask:0xf bank_mask:0xf bound_ctrl:1
	v_add_f32_dpp v50, v50, v50 row_half_mirror row_mask:0xf bank_mask:0xf bound_ctrl:1
	v_pk_mul_f32 v[72:73], v[72:73], v[100:101] op_sel_hi:[1,0]
	ds_write_b32 v115, v50
	v_add_u32_e32 v115, v115, v112
	s_waitcnt lgkmcnt(9)
	ds_read_b128 v[34:37], v113 offset:5120
	ds_read_b128 v[38:41], v113 offset:5248
	ds_read_b128 v[42:45], v113 offset:17408
	ds_read_b128 v[46:49], v113 offset:17536
	ds_read_b128 v[50:53], v113 offset:1024
	ds_read_b128 v[54:57], v113 offset:1152
	v_pk_fma_f32 v[66:67], v[102:103], v[74:75], v[66:67]
	v_pk_fma_f32 v[68:69], v[104:105], v[76:77], v[68:69]
	v_pk_fma_f32 v[70:71], v[106:107], v[78:79], v[70:71]
	v_pk_fma_f32 v[72:73], v[108:109], v[80:81], v[72:73]
	s_waitcnt lgkmcnt(14)
	v_pk_fma_f32 v[102:103], v[58:59], v[82:83], v[66:67] op_sel_hi:[0,1,1]
	v_pk_fma_f32 v[104:105], v[58:59], v[84:85], v[68:69] op_sel_hi:[0,1,1]
	v_pk_fma_f32 v[106:107], v[58:59], v[86:87], v[70:71] op_sel_hi:[0,1,1]
	v_pk_fma_f32 v[108:109], v[58:59], v[88:89], v[72:73] op_sel_hi:[0,1,1]
	s_waitcnt lgkmcnt(10)
	ds_read_b128 v[58:61], v113 offset:13568
	ds_read_b128 v[62:65], v113 offset:13696
	ds_read_b128 v[66:69], v113 offset:9472
	ds_read_b128 v[70:73], v113 offset:9600
	ds_read_b32 v100, v114 offset:21760
	v_pk_mul_f32 v[18:19], v[102:103], v[18:19]
	v_pk_mul_f32 v[90:91], v[102:103], v[90:91]
	v_pk_fma_f32 v[18:19], v[104:105], v[20:21], v[18:19]
	v_pk_fma_f32 v[90:91], v[104:105], v[92:93], v[90:91]
	v_pk_fma_f32 v[18:19], v[106:107], v[22:23], v[18:19]
	v_pk_fma_f32 v[90:91], v[106:107], v[94:95], v[90:91]
	v_pk_fma_f32 v[18:19], v[108:109], v[24:25], v[18:19]
	v_pk_fma_f32 v[90:91], v[108:109], v[96:97], v[90:91]
	v_add_f32_e32 v18, v18, v19
	v_add_f32_e32 v90, v90, v91
	s_waitcnt lgkmcnt(12)
	v_pk_mul_f32 v[26:27], v[26:27], v[98:99] op_sel_hi:[1,0]
	v_add_f32_dpp v18, v18, v18 quad_perm:[1,0,3,2] row_mask:0xf bank_mask:0xf bound_ctrl:1
	v_add_f32_dpp v90, v90, v90 quad_perm:[1,0,3,2] row_mask:0xf bank_mask:0xf bound_ctrl:1
	v_pk_mul_f32 v[28:29], v[28:29], v[98:99] op_sel_hi:[1,0]
	v_add_f32_dpp v18, v18, v18 quad_perm:[2,3,0,1] row_mask:0xf bank_mask:0xf bound_ctrl:1
	v_add_f32_dpp v90, v90, v90 quad_perm:[2,3,0,1] row_mask:0xf bank_mask:0xf bound_ctrl:1
	v_pk_mul_f32 v[30:31], v[30:31], v[98:99] op_sel_hi:[1,0]
	v_add_f32_dpp v18, v18, v18 row_half_mirror row_mask:0xf bank_mask:0xf bound_ctrl:1
	v_add_f32_dpp v90, v90, v90 row_half_mirror row_mask:0xf bank_mask:0xf bound_ctrl:1
	v_pk_mul_f32 v[32:33], v[32:33], v[98:99] op_sel_hi:[1,0]
	ds_write_b32 v115, v90
	v_add_u32_e32 v115, v115, v112
	s_waitcnt lgkmcnt(9)
; __device__ __forceinline__ float afma(float a, float b, float c) { float d; asm("v_fma_f32 %0, %1, %2, %3" : "=v"(d) : "v"(a), "v"(b), "v"(c)); return d; }
; __device__ __forceinline__ float amul(float a, float b) { float d; asm("v_mul_f32 %0, %1, %2" : "=v"(d) : "v"(a), "v"(b)); return d; }
; __device__ __forceinline__ void phase_scans(const Params& p, unsigned char* lds) {
;     ...
;                 for (int s = 0; s < 16; ++s) {
;                     const int sn = (s + 1) & 15;
;                     f32x4 r4n[2], w4n[2], k4n[2], kk4n[2], na4n[2]; float v1n;
;                     RW_OPS(sn, r4n, w4n, k4n, kk4n, na4n, v1n);
;                     float d0 = amul(S[0], kk4[0][0]), d1 = amul(S[4], kk4[1][0]);
; #pragma unroll
;                     for (int j = 1; j < 4; ++j) { d0 = afma(S[j], kk4[0][j], d0); d1 = afma(S[4 + j], kk4[1][j], d1); }
;                     const float d = dpp_sum8(d0 + d1);
; #pragma unroll
;                     for (int j = 0; j < 4; ++j) {
;                         S[j] = afma(v1, k4[0][j], afma(S[j], w4[0][j], amul(d, na4[0][j])));
;                         S[4 + j] = afma(v1, k4[1][j], afma(S[4 + j], w4[1][j], amul(d, na4[1][j]))); }
;                     float y0 = amul(S[0], r4[0][0]), y1 = amul(S[4], r4[1][0]);
; #pragma unroll
;                     for (int j = 1; j < 4; ++j) { y0 = afma(S[j], r4[0][j], y0); y1 = afma(S[4 + j], r4[1][j], y1); }
;                     const float y = dpp_sum8(y0 + y1);
;                     ydst[s * ystep] = y;
	ds_read_b128 v[74:77], v113 offset:5376
	ds_read_b128 v[78:81], v113 offset:5504
	ds_read_b128 v[82:85], v113 offset:17664
	ds_read_b128 v[86:89], v113 offset:17792
	ds_read_b128 v[90:93], v113 offset:1280
	ds_read_b128 v[94:97], v113 offset:1408
	v_pk_fma_f32 v[26:27], v[102:103], v[34:35], v[26:27]
	v_pk_fma_f32 v[28:29], v[104:105], v[36:37], v[28:29]
	v_pk_fma_f32 v[30:31], v[106:107], v[38:39], v[30:31]
	v_pk_fma_f32 v[32:33], v[108:109], v[40:41], v[32:33]
	s_waitcnt lgkmcnt(14)
	v_pk_fma_f32 v[102:103], v[18:19], v[42:43], v[26:27] op_sel_hi:[0,1,1]
	v_pk_fma_f32 v[104:105], v[18:19], v[44:45], v[28:29] op_sel_hi:[0,1,1]
	v_pk_fma_f32 v[106:107], v[18:19], v[46:47], v[30:31] op_sel_hi:[0,1,1]
	v_pk_fma_f32 v[108:109], v[18:19], v[48:49], v[32:33] op_sel_hi:[0,1,1]
	s_waitcnt lgkmcnt(10)
	ds_read_b128 v[18:21], v113 offset:13824
	ds_read_b128 v[22:25], v113 offset:13952
	ds_read_b128 v[26:29], v113 offset:9728
	ds_read_b128 v[30:33], v113 offset:9856
	ds_read_b32 v98, v114 offset:22016
	v_pk_mul_f32 v[58:59], v[102:103], v[58:59]
	v_pk_mul_f32 v[50:51], v[102:103], v[50:51]
	v_pk_fma_f32 v[58:59], v[104:105], v[60:61], v[58:59]
	v_pk_fma_f32 v[50:51], v[104:105], v[52:53], v[50:51]
	v_pk_fma_f32 v[58:59], v[106:107], v[62:63], v[58:59]
	v_pk_fma_f32 v[50:51], v[106:107], v[54:55], v[50:51]
	v_pk_fma_f32 v[58:59], v[108:109], v[64:65], v[58:59]
	v_pk_fma_f32 v[50:51], v[108:109], v[56:57], v[50:51]
	v_add_f32_e32 v58, v58, v59
	v_add_f32_e32 v50, v50, v51
	s_waitcnt lgkmcnt(12)
	v_pk_mul_f32 v[66:67], v[66:67], v[100:101] op_sel_hi:[1,0]
	v_add_f32_dpp v58, v58, v58 quad_perm:[1,0,3,2] row_mask:0xf bank_mask:0xf bound_ctrl:1
	v_add_f32_dpp v50, v50, v50 quad_perm:[1,0,3,2] row_mask:0xf bank_mask:0xf bound_ctrl:1
	v_pk_mul_f32 v[68:69], v[68:69], v[100:101] op_sel_hi:[1,0]
	v_add_f32_dpp v58, v58, v58 quad_perm:[2,3,0,1] row_mask:0xf bank_mask:0xf bound_ctrl:1
	v_add_f32_dpp v50, v50, v50 quad_perm:[2,3,0,1] row_mask:0xf bank_mask:0xf bound_ctrl:1
	v_pk_mul_f32 v[70:71], v[70:71], v[100:101] op_sel_hi:[1,0]
	v_add_f32_dpp v58, v58, v58 row_half_mirror row_mask:0xf bank_mask:0xf bound_ctrl:1
	v_add_f32_dpp v50, v50, v50 row_half_mirror row_mask:0xf bank_mask:0xf bound_ctrl:1
	v_pk_mul_f32 v[72:73], v[72:73], v[100:101] op_sel_hi:[1,0]
	ds_write_b32 v115, v50
	v_add_u32_e32 v115, v115, v112
	s_waitcnt lgkmcnt(9)
	ds_read_b128 v[34:37], v113 offset:5632
	ds_read_b128 v[38:41], v113 offset:5760
	ds_read_b128 v[42:45], v113 offset:17920
	ds_read_b128 v[46:49], v113 offset:18048
	ds_read_b128 v[50:53], v113 offset:1536
	ds_read_b128 v[54:57], v113 offset:1664
	v_pk_fma_f32 v[66:67], v[102:103], v[74:75], v[66:67]
	v_pk_fma_f32 v[68:69], v[104:105], v[76:77], v[68:69]
	v_pk_fma_f32 v[70:71], v[106:107], v[78:79], v[70:71]
	v_pk_fma_f32 v[72:73], v[108:109], v[80:81], v[72:73]
	s_waitcnt lgkmcnt(14)
	v_pk_fma_f32 v[102:103], v[58:59], v[82:83], v[66:67] op_sel_hi:[0,1,1]
	v_pk_fma_f32 v[104:105], v[58:59], v[84:85], v[68:69] op_sel_hi:[0,1,1]
	v_pk_fma_f32 v[106:107], v[58:59], v[86:87], v[70:71] op_sel_hi:[0,1,1]
	v_pk_fma_f32 v[108:109], v[58:59], v[88:89], v[72:73] op_sel_hi:[0,1,1]
	s_waitcnt lgkmcnt(10)
	ds_read_b128 v[58:61], v113 offset:14080
	ds_read_b128 v[62:65], v113 offset:14208
	ds_read_b128 v[66:69], v113 offset:9984
	ds_read_b128 v[70:73], v113 offset:10112
	ds_read_b32 v100, v114 offset:22272
	v_pk_mul_f32 v[18:19], v[102:103], v[18:19]
	v_pk_mul_f32 v[90:91], v[102:103], v[90:91]
	v_pk_fma_f32 v[18:19], v[104:105], v[20:21], v[18:19]
	v_pk_fma_f32 v[90:91], v[104:105], v[92:93], v[90:91]
	v_pk_fma_f32 v[18:19], v[106:107], v[22:23], v[18:19]
	v_pk_fma_f32 v[90:91], v[106:107], v[94:95], v[90:91]
	v_pk_fma_f32 v[18:19], v[108:109], v[24:25], v[18:19]
	v_pk_fma_f32 v[90:91], v[108:109], v[96:97], v[90:91]
	v_add_f32_e32 v18, v18, v19
	v_add_f32_e32 v90, v90, v91
	s_waitcnt lgkmcnt(12)
	v_pk_mul_f32 v[26:27], v[26:27], v[98:99] op_sel_hi:[1,0]
	v_add_f32_dpp v18, v18, v18 quad_perm:[1,0,3,2] row_mask:0xf bank_mask:0xf bound_ctrl:1
	v_add_f32_dpp v90, v90, v90 quad_perm:[1,0,3,2] row_mask:0xf bank_mask:0xf bound_ctrl:1
	v_pk_mul_f32 v[28:29], v[28:29], v[98:99] op_sel_hi:[1,0]
	v_add_f32_dpp v18, v18, v18 quad_perm:[2,3,0,1] row_mask:0xf bank_mask:0xf bound_ctrl:1
	v_add_f32_dpp v90, v90, v90 quad_perm:[2,3,0,1] row_mask:0xf bank_mask:0xf bound_ctrl:1
	v_pk_mul_f32 v[30:31], v[30:31], v[98:99] op_sel_hi:[1,0]
	v_add_f32_dpp v18, v18, v18 row_half_mirror row_mask:0xf bank_mask:0xf bound_ctrl:1
	v_add_f32_dpp v90, v90, v90 row_half_mirror row_mask:0xf bank_mask:0xf bound_ctrl:1
	v_pk_mul_f32 v[32:33], v[32:33], v[98:99] op_sel_hi:[1,0]
	ds_write_b32 v115, v90
	v_add_u32_e32 v115, v115, v112
	s_waitcnt lgkmcnt(9)
	ds_read_b128 v[74:77], v113 offset:5888
	ds_read_b128 v[78:81], v113 offset:6016
	ds_read_b128 v[82:85], v113 offset:18176
	ds_read_b128 v[86:89], v113 offset:18304
	ds_read_b128 v[90:93], v113 offset:1792
	ds_read_b128 v[94:97], v113 offset:1920
	v_pk_fma_f32 v[26:27], v[102:103], v[34:35], v[26:27]
	v_pk_fma_f32 v[28:29], v[104:105], v[36:37], v[28:29]
	v_pk_fma_f32 v[30:31], v[106:107], v[38:39], v[30:31]
	v_pk_fma_f32 v[32:33], v[108:109], v[40:41], v[32:33]
	s_waitcnt lgkmcnt(14)
	v_pk_fma_f32 v[102:103], v[18:19], v[42:43], v[26:27] op_sel_hi:[0,1,1]
	v_pk_fma_f32 v[104:105], v[18:19], v[44:45], v[28:29] op_sel_hi:[0,1,1]
	v_pk_fma_f32 v[106:107], v[18:19], v[46:47], v[30:31] op_sel_hi:[0,1,1]
	v_pk_fma_f32 v[108:109], v[18:19], v[48:49], v[32:33] op_sel_hi:[0,1,1]
	s_waitcnt lgkmcnt(10)
; __device__ __forceinline__ float afma(float a, float b, float c) { float d; asm("v_fma_f32 %0, %1, %2, %3" : "=v"(d) : "v"(a), "v"(b), "v"(c)); return d; }
; __device__ __forceinline__ float amul(float a, float b) { float d; asm("v_mul_f32 %0, %1, %2" : "=v"(d) : "v"(a), "v"(b)); return d; }
; __device__ __forceinline__ void phase_scans(const Params& p, unsigned char* lds) {
;     ...
;                 for (int s = 0; s < 16; ++s) {
;                     const int sn = (s + 1) & 15;
;                     f32x4 r4n[2], w4n[2], k4n[2], kk4n[2], na4n[2]; float v1n;
;                     RW_OPS(sn, r4n, w4n, k4n, kk4n, na4n, v1n);
;                     float d0 = amul(S[0], kk4[0][0]), d1 = amul(S[4], kk4[1][0]);
; #pragma unroll
;                     for (int j = 1; j < 4; ++j) { d0 = afma(S[j], kk4[0][j], d0); d1 = afma(S[4 + j], kk4[1][j], d1); }
;                     const float d = dpp_sum8(d0 + d1);
; #pragma unroll
;                     for (int j = 0; j < 4; ++j) {
;                         S[j] = afma(v1, k4[0][j], afma(S[j], w4[0][j], amul(d, na4[0][j])));
;                         S[4 + j] = afma(v1, k4[1][j], afma(S[4 + j], w4[1][j], amul(d, na4[1][j]))); }
;                     float y0 = amul(S[0], r4[0][0]), y1 = amul(S[4], r4[1][0]);
; #pragma unroll
;                     for (int j = 1; j < 4; ++j) { y0 = afma(S[j], r4[0][j], y0); y1 = afma(S[4 + j], r4[1][j], y1); }
;                     const float y = dpp_sum8(y0 + y1);
;                     ydst[s * ystep] = y;
	ds_read_b128 v[18:21], v113 offset:14336
	ds_read_b128 v[22:25], v113 offset:14464
	ds_read_b128 v[26:29], v113 offset:10240
	ds_read_b128 v[30:33], v113 offset:10368
	ds_read_b32 v98, v114 offset:22528
	v_pk_mul_f32 v[58:59], v[102:103], v[58:59]
	v_pk_mul_f32 v[50:51], v[102:103], v[50:51]
	v_pk_fma_f32 v[58:59], v[104:105], v[60:61], v[58:59]
	v_pk_fma_f32 v[50:51], v[104:105], v[52:53], v[50:51]
	v_pk_fma_f32 v[58:59], v[106:107], v[62:63], v[58:59]
	v_pk_fma_f32 v[50:51], v[106:107], v[54:55], v[50:51]
	v_pk_fma_f32 v[58:59], v[108:109], v[64:65], v[58:59]
	v_pk_fma_f32 v[50:51], v[108:109], v[56:57], v[50:51]
	v_add_f32_e32 v58, v58, v59
	v_add_f32_e32 v50, v50, v51
	s_waitcnt lgkmcnt(12)
	v_pk_mul_f32 v[66:67], v[66:67], v[100:101] op_sel_hi:[1,0]
	v_add_f32_dpp v58, v58, v58 quad_perm:[1,0,3,2] row_mask:0xf bank_mask:0xf bound_ctrl:1
	v_add_f32_dpp v50, v50, v50 quad_perm:[1,0,3,2] row_mask:0xf bank_mask:0xf bound_ctrl:1
	v_pk_mul_f32 v[68:69], v[68:69], v[100:101] op_sel_hi:[1,0]
	v_add_f32_dpp v58, v58, v58 quad_perm:[2,3,0,1] row_mask:0xf bank_mask:0xf bound_ctrl:1
	v_add_f32_dpp v50, v50, v50 quad_perm:[2,3,0,1] row_mask:0xf bank_mask:0xf bound_ctrl:1
	v_pk_mul_f32 v[70:71], v[70:71], v[100:101] op_sel_hi:[1,0]
	v_add_f32_dpp v58, v58, v58 row_half_mirror row_mask:0xf bank_mask:0xf bound_ctrl:1
	v_add_f32_dpp v50, v50, v50 row_half_mirror row_mask:0xf bank_mask:0xf bound_ctrl:1
	v_pk_mul_f32 v[72:73], v[72:73], v[100:101] op_sel_hi:[1,0]
	ds_write_b32 v115, v50
	v_add_u32_e32 v115, v115, v112
	s_waitcnt lgkmcnt(9)
	ds_read_b128 v[34:37], v113 offset:6144
	ds_read_b128 v[38:41], v113 offset:6272
	ds_read_b128 v[42:45], v113 offset:18432
	ds_read_b128 v[46:49], v113 offset:18560
	ds_read_b128 v[50:53], v113 offset:2048
	ds_read_b128 v[54:57], v113 offset:2176
	v_pk_fma_f32 v[66:67], v[102:103], v[74:75], v[66:67]
	v_pk_fma_f32 v[68:69], v[104:105], v[76:77], v[68:69]
	v_pk_fma_f32 v[70:71], v[106:107], v[78:79], v[70:71]
	v_pk_fma_f32 v[72:73], v[108:109], v[80:81], v[72:73]
	s_waitcnt lgkmcnt(14)
	v_pk_fma_f32 v[102:103], v[58:59], v[82:83], v[66:67] op_sel_hi:[0,1,1]
	v_pk_fma_f32 v[104:105], v[58:59], v[84:85], v[68:69] op_sel_hi:[0,1,1]
	v_pk_fma_f32 v[106:107], v[58:59], v[86:87], v[70:71] op_sel_hi:[0,1,1]
	v_pk_fma_f32 v[108:109], v[58:59], v[88:89], v[72:73] op_sel_hi:[0,1,1]
	s_waitcnt lgkmcnt(10)
	ds_read_b128 v[58:61], v113 offset:14592
	ds_read_b128 v[62:65], v113 offset:14720
	ds_read_b128 v[66:69], v113 offset:10496
	ds_read_b128 v[70:73], v113 offset:10624
	ds_read_b32 v100, v114 offset:22784
	v_pk_mul_f32 v[18:19], v[102:103], v[18:19]
	v_pk_mul_f32 v[90:91], v[102:103], v[90:91]
	v_pk_fma_f32 v[18:19], v[104:105], v[20:21], v[18:19]
	v_pk_fma_f32 v[90:91], v[104:105], v[92:93], v[90:91]
	v_pk_fma_f32 v[18:19], v[106:107], v[22:23], v[18:19]
	v_pk_fma_f32 v[90:91], v[106:107], v[94:95], v[90:91]
	v_pk_fma_f32 v[18:19], v[108:109], v[24:25], v[18:19]
	v_pk_fma_f32 v[90:91], v[108:109], v[96:97], v[90:91]
	v_add_f32_e32 v18, v18, v19
	v_add_f32_e32 v90, v90, v91
	s_waitcnt lgkmcnt(12)
	v_pk_mul_f32 v[26:27], v[26:27], v[98:99] op_sel_hi:[1,0]
	v_add_f32_dpp v18, v18, v18 quad_perm:[1,0,3,2] row_mask:0xf bank_mask:0xf bound_ctrl:1
	v_add_f32_dpp v90, v90, v90 quad_perm:[1,0,3,2] row_mask:0xf bank_mask:0xf bound_ctrl:1
	v_pk_mul_f32 v[28:29], v[28:29], v[98:99] op_sel_hi:[1,0]
	v_add_f32_dpp v18, v18, v18 quad_perm:[2,3,0,1] row_mask:0xf bank_mask:0xf bound_ctrl:1
	v_add_f32_dpp v90, v90, v90 quad_perm:[2,3,0,1] row_mask:0xf bank_mask:0xf bound_ctrl:1
	v_pk_mul_f32 v[30:31], v[30:31], v[98:99] op_sel_hi:[1,0]
	v_add_f32_dpp v18, v18, v18 row_half_mirror row_mask:0xf bank_mask:0xf bound_ctrl:1
	v_add_f32_dpp v90, v90, v90 row_half_mirror row_mask:0xf bank_mask:0xf bound_ctrl:1
	v_pk_mul_f32 v[32:33], v[32:33], v[98:99] op_sel_hi:[1,0]
	ds_write_b32 v115, v90
	v_add_u32_e32 v115, v115, v112
	s_waitcnt lgkmcnt(9)
	ds_read_b128 v[74:77], v113 offset:6400
	ds_read_b128 v[78:81], v113 offset:6528
	ds_read_b128 v[82:85], v113 offset:18688
	ds_read_b128 v[86:89], v113 offset:18816
	ds_read_b128 v[90:93], v113 offset:2304
	ds_read_b128 v[94:97], v113 offset:2432
	v_pk_fma_f32 v[26:27], v[102:103], v[34:35], v[26:27]
	v_pk_fma_f32 v[28:29], v[104:105], v[36:37], v[28:29]
	v_pk_fma_f32 v[30:31], v[106:107], v[38:39], v[30:31]
	v_pk_fma_f32 v[32:33], v[108:109], v[40:41], v[32:33]
	s_waitcnt lgkmcnt(14)
	v_pk_fma_f32 v[102:103], v[18:19], v[42:43], v[26:27] op_sel_hi:[0,1,1]
	v_pk_fma_f32 v[104:105], v[18:19], v[44:45], v[28:29] op_sel_hi:[0,1,1]
	v_pk_fma_f32 v[106:107], v[18:19], v[46:47], v[30:31] op_sel_hi:[0,1,1]
	v_pk_fma_f32 v[108:109], v[18:19], v[48:49], v[32:33] op_sel_hi:[0,1,1]
	s_waitcnt lgkmcnt(10)
	ds_read_b128 v[18:21], v113 offset:14848
	ds_read_b128 v[22:25], v113 offset:14976
	ds_read_b128 v[26:29], v113 offset:10752
	ds_read_b128 v[30:33], v113 offset:10880
	ds_read_b32 v98, v114 offset:23040
	v_pk_mul_f32 v[58:59], v[102:103], v[58:59]
	v_pk_mul_f32 v[50:51], v[102:103], v[50:51]
	v_pk_fma_f32 v[58:59], v[104:105], v[60:61], v[58:59]
	v_pk_fma_f32 v[50:51], v[104:105], v[52:53], v[50:51]
	v_pk_fma_f32 v[58:59], v[106:107], v[62:63], v[58:59]
	v_pk_fma_f32 v[50:51], v[106:107], v[54:55], v[50:51]
	v_pk_fma_f32 v[58:59], v[108:109], v[64:65], v[58:59]
	v_pk_fma_f32 v[50:51], v[108:109], v[56:57], v[50:51]
	v_add_f32_e32 v58, v58, v59
	v_add_f32_e32 v50, v50, v51
	s_waitcnt lgkmcnt(12)
; __device__ __forceinline__ float afma(float a, float b, float c) { float d; asm("v_fma_f32 %0, %1, %2, %3" : "=v"(d) : "v"(a), "v"(b), "v"(c)); return d; }
; __device__ __forceinline__ float amul(float a, float b) { float d; asm("v_mul_f32 %0, %1, %2" : "=v"(d) : "v"(a), "v"(b)); return d; }
; __device__ __forceinline__ void phase_scans(const Params& p, unsigned char* lds) {
;     ...
;                 for (int s = 0; s < 16; ++s) {
;                     const int sn = (s + 1) & 15;
;                     f32x4 r4n[2], w4n[2], k4n[2], kk4n[2], na4n[2]; float v1n;
;                     RW_OPS(sn, r4n, w4n, k4n, kk4n, na4n, v1n);
;                     float d0 = amul(S[0], kk4[0][0]), d1 = amul(S[4], kk4[1][0]);
; #pragma unroll
;                     for (int j = 1; j < 4; ++j) { d0 = afma(S[j], kk4[0][j], d0); d1 = afma(S[4 + j], kk4[1][j], d1); }
;                     const float d = dpp_sum8(d0 + d1);
; #pragma unroll
;                     for (int j = 0; j < 4; ++j) {
;                         S[j] = afma(v1, k4[0][j], afma(S[j], w4[0][j], amul(d, na4[0][j])));
;                         S[4 + j] = afma(v1, k4[1][j], afma(S[4 + j], w4[1][j], amul(d, na4[1][j]))); }
;                     float y0 = amul(S[0], r4[0][0]), y1 = amul(S[4], r4[1][0]);
; #pragma unroll
;                     for (int j = 1; j < 4; ++j) { y0 = afma(S[j], r4[0][j], y0); y1 = afma(S[4 + j], r4[1][j], y1); }
;                     const float y = dpp_sum8(y0 + y1);
;                     ydst[s * ystep] = y;
	v_pk_mul_f32 v[66:67], v[66:67], v[100:101] op_sel_hi:[1,0]
	v_add_f32_dpp v58, v58, v58 quad_perm:[1,0,3,2] row_mask:0xf bank_mask:0xf bound_ctrl:1
	v_add_f32_dpp v50, v50, v50 quad_perm:[1,0,3,2] row_mask:0xf bank_mask:0xf bound_ctrl:1
	v_pk_mul_f32 v[68:69], v[68:69], v[100:101] op_sel_hi:[1,0]
	v_add_f32_dpp v58, v58, v58 quad_perm:[2,3,0,1] row_mask:0xf bank_mask:0xf bound_ctrl:1
	v_add_f32_dpp v50, v50, v50 quad_perm:[2,3,0,1] row_mask:0xf bank_mask:0xf bound_ctrl:1
	v_pk_mul_f32 v[70:71], v[70:71], v[100:101] op_sel_hi:[1,0]
	v_add_f32_dpp v58, v58, v58 row_half_mirror row_mask:0xf bank_mask:0xf bound_ctrl:1
	v_add_f32_dpp v50, v50, v50 row_half_mirror row_mask:0xf bank_mask:0xf bound_ctrl:1
	v_pk_mul_f32 v[72:73], v[72:73], v[100:101] op_sel_hi:[1,0]
	ds_write_b32 v115, v50
	v_add_u32_e32 v115, v115, v112
	s_waitcnt lgkmcnt(9)
	ds_read_b128 v[34:37], v113 offset:6656
	ds_read_b128 v[38:41], v113 offset:6784
	ds_read_b128 v[42:45], v113 offset:18944
	ds_read_b128 v[46:49], v113 offset:19072
	ds_read_b128 v[50:53], v113 offset:2560
	ds_read_b128 v[54:57], v113 offset:2688
	v_pk_fma_f32 v[66:67], v[102:103], v[74:75], v[66:67]
	v_pk_fma_f32 v[68:69], v[104:105], v[76:77], v[68:69]
	v_pk_fma_f32 v[70:71], v[106:107], v[78:79], v[70:71]
	v_pk_fma_f32 v[72:73], v[108:109], v[80:81], v[72:73]
	s_waitcnt lgkmcnt(14)
	v_pk_fma_f32 v[102:103], v[58:59], v[82:83], v[66:67] op_sel_hi:[0,1,1]
	v_pk_fma_f32 v[104:105], v[58:59], v[84:85], v[68:69] op_sel_hi:[0,1,1]
	v_pk_fma_f32 v[106:107], v[58:59], v[86:87], v[70:71] op_sel_hi:[0,1,1]
	v_pk_fma_f32 v[108:109], v[58:59], v[88:89], v[72:73] op_sel_hi:[0,1,1]
	s_waitcnt lgkmcnt(10)
	ds_read_b128 v[58:61], v113 offset:15104
	ds_read_b128 v[62:65], v113 offset:15232
	ds_read_b128 v[66:69], v113 offset:11008
	ds_read_b128 v[70:73], v113 offset:11136
	ds_read_b32 v100, v114 offset:23296
	v_pk_mul_f32 v[18:19], v[102:103], v[18:19]
	v_pk_mul_f32 v[90:91], v[102:103], v[90:91]
	v_pk_fma_f32 v[18:19], v[104:105], v[20:21], v[18:19]
	v_pk_fma_f32 v[90:91], v[104:105], v[92:93], v[90:91]
	v_pk_fma_f32 v[18:19], v[106:107], v[22:23], v[18:19]
	v_pk_fma_f32 v[90:91], v[106:107], v[94:95], v[90:91]
	v_pk_fma_f32 v[18:19], v[108:109], v[24:25], v[18:19]
	v_pk_fma_f32 v[90:91], v[108:109], v[96:97], v[90:91]
	v_add_f32_e32 v18, v18, v19
	v_add_f32_e32 v90, v90, v91
	s_waitcnt lgkmcnt(12)
	v_pk_mul_f32 v[26:27], v[26:27], v[98:99] op_sel_hi:[1,0]
	v_add_f32_dpp v18, v18, v18 quad_perm:[1,0,3,2] row_mask:0xf bank_mask:0xf bound_ctrl:1
	v_add_f32_dpp v90, v90, v90 quad_perm:[1,0,3,2] row_mask:0xf bank_mask:0xf bound_ctrl:1
	v_pk_mul_f32 v[28:29], v[28:29], v[98:99] op_sel_hi:[1,0]
	v_add_f32_dpp v18, v18, v18 quad_perm:[2,3,0,1] row_mask:0xf bank_mask:0xf bound_ctrl:1
	v_add_f32_dpp v90, v90, v90 quad_perm:[2,3,0,1] row_mask:0xf bank_mask:0xf bound_ctrl:1
	v_pk_mul_f32 v[30:31], v[30:31], v[98:99] op_sel_hi:[1,0]
	v_add_f32_dpp v18, v18, v18 row_half_mirror row_mask:0xf bank_mask:0xf bound_ctrl:1
	v_add_f32_dpp v90, v90, v90 row_half_mirror row_mask:0xf bank_mask:0xf bound_ctrl:1
	v_pk_mul_f32 v[32:33], v[32:33], v[98:99] op_sel_hi:[1,0]
	ds_write_b32 v115, v90
	v_add_u32_e32 v115, v115, v112
	s_waitcnt lgkmcnt(9)
	ds_read_b128 v[74:77], v113 offset:6912
	ds_read_b128 v[78:81], v113 offset:7040
	ds_read_b128 v[82:85], v113 offset:19200
	ds_read_b128 v[86:89], v113 offset:19328
	ds_read_b128 v[90:93], v113 offset:2816
	ds_read_b128 v[94:97], v113 offset:2944
	v_pk_fma_f32 v[26:27], v[102:103], v[34:35], v[26:27]
	v_pk_fma_f32 v[28:29], v[104:105], v[36:37], v[28:29]
	v_pk_fma_f32 v[30:31], v[106:107], v[38:39], v[30:31]
	v_pk_fma_f32 v[32:33], v[108:109], v[40:41], v[32:33]
	s_waitcnt lgkmcnt(14)
	v_pk_fma_f32 v[102:103], v[18:19], v[42:43], v[26:27] op_sel_hi:[0,1,1]
	v_pk_fma_f32 v[104:105], v[18:19], v[44:45], v[28:29] op_sel_hi:[0,1,1]
	v_pk_fma_f32 v[106:107], v[18:19], v[46:47], v[30:31] op_sel_hi:[0,1,1]
	v_pk_fma_f32 v[108:109], v[18:19], v[48:49], v[32:33] op_sel_hi:[0,1,1]
	s_waitcnt lgkmcnt(10)
	ds_read_b128 v[18:21], v113 offset:15360
	ds_read_b128 v[22:25], v113 offset:15488
	ds_read_b128 v[26:29], v113 offset:11264
	ds_read_b128 v[30:33], v113 offset:11392
	ds_read_b32 v98, v114 offset:23552
	v_pk_mul_f32 v[58:59], v[102:103], v[58:59]
	v_pk_mul_f32 v[50:51], v[102:103], v[50:51]
	v_pk_fma_f32 v[58:59], v[104:105], v[60:61], v[58:59]
	v_pk_fma_f32 v[50:51], v[104:105], v[52:53], v[50:51]
	v_pk_fma_f32 v[58:59], v[106:107], v[62:63], v[58:59]
	v_pk_fma_f32 v[50:51], v[106:107], v[54:55], v[50:51]
	v_pk_fma_f32 v[58:59], v[108:109], v[64:65], v[58:59]
	v_pk_fma_f32 v[50:51], v[108:109], v[56:57], v[50:51]
	v_add_f32_e32 v58, v58, v59
	v_add_f32_e32 v50, v50, v51
	s_waitcnt lgkmcnt(12)
	v_pk_mul_f32 v[66:67], v[66:67], v[100:101] op_sel_hi:[1,0]
	v_add_f32_dpp v58, v58, v58 quad_perm:[1,0,3,2] row_mask:0xf bank_mask:0xf bound_ctrl:1
	v_add_f32_dpp v50, v50, v50 quad_perm:[1,0,3,2] row_mask:0xf bank_mask:0xf bound_ctrl:1
	v_pk_mul_f32 v[68:69], v[68:69], v[100:101] op_sel_hi:[1,0]
	v_add_f32_dpp v58, v58, v58 quad_perm:[2,3,0,1] row_mask:0xf bank_mask:0xf bound_ctrl:1
	v_add_f32_dpp v50, v50, v50 quad_perm:[2,3,0,1] row_mask:0xf bank_mask:0xf bound_ctrl:1
	v_pk_mul_f32 v[70:71], v[70:71], v[100:101] op_sel_hi:[1,0]
	v_add_f32_dpp v58, v58, v58 row_half_mirror row_mask:0xf bank_mask:0xf bound_ctrl:1
	v_add_f32_dpp v50, v50, v50 row_half_mirror row_mask:0xf bank_mask:0xf bound_ctrl:1
	v_pk_mul_f32 v[72:73], v[72:73], v[100:101] op_sel_hi:[1,0]
	ds_write_b32 v115, v50
	v_add_u32_e32 v115, v115, v112
	s_waitcnt lgkmcnt(9)
; __device__ __forceinline__ float afma(float a, float b, float c) { float d; asm("v_fma_f32 %0, %1, %2, %3" : "=v"(d) : "v"(a), "v"(b), "v"(c)); return d; }
; __device__ __forceinline__ float amul(float a, float b) { float d; asm("v_mul_f32 %0, %1, %2" : "=v"(d) : "v"(a), "v"(b)); return d; }
; __device__ __forceinline__ void phase_scans(const Params& p, unsigned char* lds) {
;     ...
;                 for (int s = 0; s < 16; ++s) {
;                     const int sn = (s + 1) & 15;
;                     f32x4 r4n[2], w4n[2], k4n[2], kk4n[2], na4n[2]; float v1n;
;                     RW_OPS(sn, r4n, w4n, k4n, kk4n, na4n, v1n);
;                     float d0 = amul(S[0], kk4[0][0]), d1 = amul(S[4], kk4[1][0]);
; #pragma unroll
;                     for (int j = 1; j < 4; ++j) { d0 = afma(S[j], kk4[0][j], d0); d1 = afma(S[4 + j], kk4[1][j], d1); }
;                     const float d = dpp_sum8(d0 + d1);
; #pragma unroll
;                     for (int j = 0; j < 4; ++j) {
;                         S[j] = afma(v1, k4[0][j], afma(S[j], w4[0][j], amul(d, na4[0][j])));
;                         S[4 + j] = afma(v1, k4[1][j], afma(S[4 + j], w4[1][j], amul(d, na4[1][j]))); }
;                     float y0 = amul(S[0], r4[0][0]), y1 = amul(S[4], r4[1][0]);
; #pragma unroll
;                     for (int j = 1; j < 4; ++j) { y0 = afma(S[j], r4[0][j], y0); y1 = afma(S[4 + j], r4[1][j], y1); }
;                     const float y = dpp_sum8(y0 + y1);
;                     ydst[s * ystep] = y;
	ds_read_b128 v[34:37], v113 offset:7168
	ds_read_b128 v[38:41], v113 offset:7296
	ds_read_b128 v[42:45], v113 offset:19456
	ds_read_b128 v[46:49], v113 offset:19584
	ds_read_b128 v[50:53], v113 offset:3072
	ds_read_b128 v[54:57], v113 offset:3200
	v_pk_fma_f32 v[66:67], v[102:103], v[74:75], v[66:67]
	v_pk_fma_f32 v[68:69], v[104:105], v[76:77], v[68:69]
	v_pk_fma_f32 v[70:71], v[106:107], v[78:79], v[70:71]
	v_pk_fma_f32 v[72:73], v[108:109], v[80:81], v[72:73]
	s_waitcnt lgkmcnt(14)
	v_pk_fma_f32 v[102:103], v[58:59], v[82:83], v[66:67] op_sel_hi:[0,1,1]
	v_pk_fma_f32 v[104:105], v[58:59], v[84:85], v[68:69] op_sel_hi:[0,1,1]
	v_pk_fma_f32 v[106:107], v[58:59], v[86:87], v[70:71] op_sel_hi:[0,1,1]
	v_pk_fma_f32 v[108:109], v[58:59], v[88:89], v[72:73] op_sel_hi:[0,1,1]
	s_waitcnt lgkmcnt(10)
	ds_read_b128 v[58:61], v113 offset:15616
	ds_read_b128 v[62:65], v113 offset:15744
	ds_read_b128 v[66:69], v113 offset:11520
	ds_read_b128 v[70:73], v113 offset:11648
	ds_read_b32 v100, v114 offset:23808
	v_pk_mul_f32 v[18:19], v[102:103], v[18:19]
	v_pk_mul_f32 v[90:91], v[102:103], v[90:91]
	v_pk_fma_f32 v[18:19], v[104:105], v[20:21], v[18:19]
	v_pk_fma_f32 v[90:91], v[104:105], v[92:93], v[90:91]
	v_pk_fma_f32 v[18:19], v[106:107], v[22:23], v[18:19]
	v_pk_fma_f32 v[90:91], v[106:107], v[94:95], v[90:91]
	v_pk_fma_f32 v[18:19], v[108:109], v[24:25], v[18:19]
	v_pk_fma_f32 v[90:91], v[108:109], v[96:97], v[90:91]
	v_add_f32_e32 v18, v18, v19
	v_add_f32_e32 v90, v90, v91
	s_waitcnt lgkmcnt(12)
	v_pk_mul_f32 v[26:27], v[26:27], v[98:99] op_sel_hi:[1,0]
	v_add_f32_dpp v18, v18, v18 quad_perm:[1,0,3,2] row_mask:0xf bank_mask:0xf bound_ctrl:1
	v_add_f32_dpp v90, v90, v90 quad_perm:[1,0,3,2] row_mask:0xf bank_mask:0xf bound_ctrl:1
	v_pk_mul_f32 v[28:29], v[28:29], v[98:99] op_sel_hi:[1,0]
	v_add_f32_dpp v18, v18, v18 quad_perm:[2,3,0,1] row_mask:0xf bank_mask:0xf bound_ctrl:1
	v_add_f32_dpp v90, v90, v90 quad_perm:[2,3,0,1] row_mask:0xf bank_mask:0xf bound_ctrl:1
	v_pk_mul_f32 v[30:31], v[30:31], v[98:99] op_sel_hi:[1,0]
	v_add_f32_dpp v18, v18, v18 row_half_mirror row_mask:0xf bank_mask:0xf bound_ctrl:1
	v_add_f32_dpp v90, v90, v90 row_half_mirror row_mask:0xf bank_mask:0xf bound_ctrl:1
	v_pk_mul_f32 v[32:33], v[32:33], v[98:99] op_sel_hi:[1,0]
	ds_write_b32 v115, v90
	v_add_u32_e32 v115, v115, v112
	s_waitcnt lgkmcnt(9)
	ds_read_b128 v[74:77], v113 offset:7424
	ds_read_b128 v[78:81], v113 offset:7552
	ds_read_b128 v[82:85], v113 offset:19712
	ds_read_b128 v[86:89], v113 offset:19840
	ds_read_b128 v[90:93], v113 offset:3328
	ds_read_b128 v[94:97], v113 offset:3456
	v_pk_fma_f32 v[26:27], v[102:103], v[34:35], v[26:27]
	v_pk_fma_f32 v[28:29], v[104:105], v[36:37], v[28:29]
	v_pk_fma_f32 v[30:31], v[106:107], v[38:39], v[30:31]
	v_pk_fma_f32 v[32:33], v[108:109], v[40:41], v[32:33]
	s_waitcnt lgkmcnt(14)
	v_pk_fma_f32 v[102:103], v[18:19], v[42:43], v[26:27] op_sel_hi:[0,1,1]
	v_pk_fma_f32 v[104:105], v[18:19], v[44:45], v[28:29] op_sel_hi:[0,1,1]
	v_pk_fma_f32 v[106:107], v[18:19], v[46:47], v[30:31] op_sel_hi:[0,1,1]
	v_pk_fma_f32 v[108:109], v[18:19], v[48:49], v[32:33] op_sel_hi:[0,1,1]
	s_waitcnt lgkmcnt(10)
	ds_read_b128 v[18:21], v113 offset:15872
	ds_read_b128 v[22:25], v113 offset:16000
	ds_read_b128 v[26:29], v113 offset:11776
	ds_read_b128 v[30:33], v113 offset:11904
	ds_read_b32 v98, v114 offset:24064
	v_pk_mul_f32 v[58:59], v[102:103], v[58:59]
	v_pk_mul_f32 v[50:51], v[102:103], v[50:51]
	v_pk_fma_f32 v[58:59], v[104:105], v[60:61], v[58:59]
	v_pk_fma_f32 v[50:51], v[104:105], v[52:53], v[50:51]
	v_pk_fma_f32 v[58:59], v[106:107], v[62:63], v[58:59]
	v_pk_fma_f32 v[50:51], v[106:107], v[54:55], v[50:51]
	v_pk_fma_f32 v[58:59], v[108:109], v[64:65], v[58:59]
	v_pk_fma_f32 v[50:51], v[108:109], v[56:57], v[50:51]
	v_add_f32_e32 v58, v58, v59
	v_add_f32_e32 v50, v50, v51
	s_waitcnt lgkmcnt(12)
	v_pk_mul_f32 v[66:67], v[66:67], v[100:101] op_sel_hi:[1,0]
	v_add_f32_dpp v58, v58, v58 quad_perm:[1,0,3,2] row_mask:0xf bank_mask:0xf bound_ctrl:1
	v_add_f32_dpp v50, v50, v50 quad_perm:[1,0,3,2] row_mask:0xf bank_mask:0xf bound_ctrl:1
	v_pk_mul_f32 v[68:69], v[68:69], v[100:101] op_sel_hi:[1,0]
	v_add_f32_dpp v58, v58, v58 quad_perm:[2,3,0,1] row_mask:0xf bank_mask:0xf bound_ctrl:1
	v_add_f32_dpp v50, v50, v50 quad_perm:[2,3,0,1] row_mask:0xf bank_mask:0xf bound_ctrl:1
	v_pk_mul_f32 v[70:71], v[70:71], v[100:101] op_sel_hi:[1,0]
	v_add_f32_dpp v58, v58, v58 row_half_mirror row_mask:0xf bank_mask:0xf bound_ctrl:1
	v_add_f32_dpp v50, v50, v50 row_half_mirror row_mask:0xf bank_mask:0xf bound_ctrl:1
	v_pk_mul_f32 v[72:73], v[72:73], v[100:101] op_sel_hi:[1,0]
	ds_write_b32 v115, v50
	v_add_u32_e32 v115, v115, v112
	s_waitcnt lgkmcnt(9)
	ds_read_b128 v[34:37], v113 offset:7680
	ds_read_b128 v[38:41], v113 offset:7808
	ds_read_b128 v[42:45], v113 offset:19968
	ds_read_b128 v[46:49], v113 offset:20096
	ds_read_b128 v[50:53], v113 offset:3584
	ds_read_b128 v[54:57], v113 offset:3712
	v_pk_fma_f32 v[66:67], v[102:103], v[74:75], v[66:67]
	v_pk_fma_f32 v[68:69], v[104:105], v[76:77], v[68:69]
	v_pk_fma_f32 v[70:71], v[106:107], v[78:79], v[70:71]
	v_pk_fma_f32 v[72:73], v[108:109], v[80:81], v[72:73]
	s_waitcnt lgkmcnt(14)
	v_pk_fma_f32 v[102:103], v[58:59], v[82:83], v[66:67] op_sel_hi:[0,1,1]
	v_pk_fma_f32 v[104:105], v[58:59], v[84:85], v[68:69] op_sel_hi:[0,1,1]
	v_pk_fma_f32 v[106:107], v[58:59], v[86:87], v[70:71] op_sel_hi:[0,1,1]
	v_pk_fma_f32 v[108:109], v[58:59], v[88:89], v[72:73] op_sel_hi:[0,1,1]
	s_waitcnt lgkmcnt(10)
; #define SC_BAR() do { asm volatile("s_waitcnt lgkmcnt(0)" ::: "memory"); __builtin_amdgcn_s_barrier(); asm volatile("" ::: "memory"); } while (0)
; __device__ __forceinline__ float afma(float a, float b, float c) { float d; asm("v_fma_f32 %0, %1, %2, %3" : "=v"(d) : "v"(a), "v"(b), "v"(c)); return d; }
; __device__ __forceinline__ float amul(float a, float b) { float d; asm("v_mul_f32 %0, %1, %2" : "=v"(d) : "v"(a), "v"(b)); return d; }
; __device__ __forceinline__ void phase_scans(const Params& p, unsigned char* lds) {
;     ...
;                 for (int s = 0; s < 16; ++s) {
;                     const int sn = (s + 1) & 15;
;                     f32x4 r4n[2], w4n[2], k4n[2], kk4n[2], na4n[2]; float v1n;
;                     RW_OPS(sn, r4n, w4n, k4n, kk4n, na4n, v1n);
;                     float d0 = amul(S[0], kk4[0][0]), d1 = amul(S[4], kk4[1][0]);
; #pragma unroll
;                     for (int j = 1; j < 4; ++j) { d0 = afma(S[j], kk4[0][j], d0); d1 = afma(S[4 + j], kk4[1][j], d1); }
;                     const float d = dpp_sum8(d0 + d1);
; #pragma unroll
;                     for (int j = 0; j < 4; ++j) {
;                         S[j] = afma(v1, k4[0][j], afma(S[j], w4[0][j], amul(d, na4[0][j])));
;                         S[4 + j] = afma(v1, k4[1][j], afma(S[4 + j], w4[1][j], amul(d, na4[1][j]))); }
;                     float y0 = amul(S[0], r4[0][0]), y1 = amul(S[4], r4[1][0]);
; #pragma unroll
;                     for (int j = 1; j < 4; ++j) { y0 = afma(S[j], r4[0][j], y0); y1 = afma(S[4 + j], r4[1][j], y1); }
;                     const float y = dpp_sum8(y0 + y1);
;                     ydst[s * ystep] = y;
; #pragma unroll
;                     for (int q = 0; q < 2; ++q) { r4[q] = r4n[q]; w4[q] = w4n[q]; k4[q] = k4n[q]; kk4[q] = kk4n[q]; na4[q] = na4n[q]; }
;                     v1 = v1n;
;                 }
;     ...
;                 SC_BAR();
;             }
	ds_read_b128 v[58:61], v113 offset:16128
	ds_read_b128 v[62:65], v113 offset:16256
	ds_read_b128 v[66:69], v113 offset:12032
	ds_read_b128 v[70:73], v113 offset:12160
	ds_read_b32 v100, v114 offset:24320
	v_pk_mul_f32 v[18:19], v[102:103], v[18:19]
	v_pk_mul_f32 v[90:91], v[102:103], v[90:91]
	v_pk_fma_f32 v[18:19], v[104:105], v[20:21], v[18:19]
	v_pk_fma_f32 v[90:91], v[104:105], v[92:93], v[90:91]
	v_pk_fma_f32 v[18:19], v[106:107], v[22:23], v[18:19]
	v_pk_fma_f32 v[90:91], v[106:107], v[94:95], v[90:91]
	v_pk_fma_f32 v[18:19], v[108:109], v[24:25], v[18:19]
	v_pk_fma_f32 v[90:91], v[108:109], v[96:97], v[90:91]
	v_add_f32_e32 v18, v18, v19
	v_add_f32_e32 v90, v90, v91
	s_waitcnt lgkmcnt(12)
	v_pk_mul_f32 v[26:27], v[26:27], v[98:99] op_sel_hi:[1,0]
	v_add_f32_dpp v18, v18, v18 quad_perm:[1,0,3,2] row_mask:0xf bank_mask:0xf bound_ctrl:1
	v_add_f32_dpp v90, v90, v90 quad_perm:[1,0,3,2] row_mask:0xf bank_mask:0xf bound_ctrl:1
	v_pk_mul_f32 v[28:29], v[28:29], v[98:99] op_sel_hi:[1,0]
	v_add_f32_dpp v18, v18, v18 quad_perm:[2,3,0,1] row_mask:0xf bank_mask:0xf bound_ctrl:1
	v_add_f32_dpp v90, v90, v90 quad_perm:[2,3,0,1] row_mask:0xf bank_mask:0xf bound_ctrl:1
	v_pk_mul_f32 v[30:31], v[30:31], v[98:99] op_sel_hi:[1,0]
	v_add_f32_dpp v18, v18, v18 row_half_mirror row_mask:0xf bank_mask:0xf bound_ctrl:1
	v_add_f32_dpp v90, v90, v90 row_half_mirror row_mask:0xf bank_mask:0xf bound_ctrl:1
	v_pk_mul_f32 v[32:33], v[32:33], v[98:99] op_sel_hi:[1,0]
	ds_write_b32 v115, v90
	v_add_u32_e32 v115, v115, v112
	s_waitcnt lgkmcnt(9)
	ds_read_b128 v[74:77], v113 offset:7936
	ds_read_b128 v[78:81], v113 offset:8064
	ds_read_b128 v[82:85], v113 offset:20224
	ds_read_b128 v[86:89], v113 offset:20352
	ds_read_b128 v[90:93], v113 offset:3840
	ds_read_b128 v[94:97], v113 offset:3968
	v_pk_fma_f32 v[26:27], v[102:103], v[34:35], v[26:27]
	v_pk_fma_f32 v[28:29], v[104:105], v[36:37], v[28:29]
	v_pk_fma_f32 v[30:31], v[106:107], v[38:39], v[30:31]
	v_pk_fma_f32 v[32:33], v[108:109], v[40:41], v[32:33]
	s_waitcnt lgkmcnt(14)
	v_pk_fma_f32 v[102:103], v[18:19], v[42:43], v[26:27] op_sel_hi:[0,1,1]
	v_pk_fma_f32 v[104:105], v[18:19], v[44:45], v[28:29] op_sel_hi:[0,1,1]
	v_pk_fma_f32 v[106:107], v[18:19], v[46:47], v[30:31] op_sel_hi:[0,1,1]
	v_pk_fma_f32 v[108:109], v[18:19], v[48:49], v[32:33] op_sel_hi:[0,1,1]
	s_waitcnt lgkmcnt(10)
	v_pk_mul_f32 v[58:59], v[102:103], v[58:59]
	v_pk_mul_f32 v[50:51], v[102:103], v[50:51]
	v_pk_fma_f32 v[58:59], v[104:105], v[60:61], v[58:59]
	v_pk_fma_f32 v[50:51], v[104:105], v[52:53], v[50:51]
	v_pk_fma_f32 v[58:59], v[106:107], v[62:63], v[58:59]
	v_pk_fma_f32 v[50:51], v[106:107], v[54:55], v[50:51]
	v_pk_fma_f32 v[58:59], v[108:109], v[64:65], v[58:59]
	v_pk_fma_f32 v[50:51], v[108:109], v[56:57], v[50:51]
	v_add_f32_e32 v58, v58, v59
	v_add_f32_e32 v50, v50, v51
	s_waitcnt lgkmcnt(7)
	v_pk_mul_f32 v[66:67], v[66:67], v[100:101] op_sel_hi:[1,0]
	v_add_f32_dpp v58, v58, v58 quad_perm:[1,0,3,2] row_mask:0xf bank_mask:0xf bound_ctrl:1
	v_add_f32_dpp v50, v50, v50 quad_perm:[1,0,3,2] row_mask:0xf bank_mask:0xf bound_ctrl:1
	v_pk_mul_f32 v[68:69], v[68:69], v[100:101] op_sel_hi:[1,0]
	v_add_f32_dpp v58, v58, v58 quad_perm:[2,3,0,1] row_mask:0xf bank_mask:0xf bound_ctrl:1
	v_add_f32_dpp v50, v50, v50 quad_perm:[2,3,0,1] row_mask:0xf bank_mask:0xf bound_ctrl:1
	v_pk_mul_f32 v[70:71], v[70:71], v[100:101] op_sel_hi:[1,0]
	v_add_f32_dpp v58, v58, v58 row_half_mirror row_mask:0xf bank_mask:0xf bound_ctrl:1
	v_add_f32_dpp v50, v50, v50 row_half_mirror row_mask:0xf bank_mask:0xf bound_ctrl:1
	v_pk_mul_f32 v[72:73], v[72:73], v[100:101] op_sel_hi:[1,0]
	ds_write_b32 v115, v50
	v_add_u32_e32 v115, v115, v112
	s_waitcnt lgkmcnt(5)
	v_pk_fma_f32 v[66:67], v[102:103], v[74:75], v[66:67]
	v_pk_fma_f32 v[68:69], v[104:105], v[76:77], v[68:69]
	v_pk_fma_f32 v[70:71], v[106:107], v[78:79], v[70:71]
	v_pk_fma_f32 v[72:73], v[108:109], v[80:81], v[72:73]
	s_waitcnt lgkmcnt(3)
	v_pk_fma_f32 v[102:103], v[58:59], v[82:83], v[66:67] op_sel_hi:[0,1,1]
	v_pk_fma_f32 v[104:105], v[58:59], v[84:85], v[68:69] op_sel_hi:[0,1,1]
	v_pk_fma_f32 v[106:107], v[58:59], v[86:87], v[70:71] op_sel_hi:[0,1,1]
	v_pk_fma_f32 v[108:109], v[58:59], v[88:89], v[72:73] op_sel_hi:[0,1,1]
	s_waitcnt lgkmcnt(1)
	v_pk_mul_f32 v[90:91], v[102:103], v[90:91]
	v_pk_fma_f32 v[90:91], v[104:105], v[92:93], v[90:91]
	v_pk_fma_f32 v[90:91], v[106:107], v[94:95], v[90:91]
	v_pk_fma_f32 v[90:91], v[108:109], v[96:97], v[90:91]
	v_add_f32_e32 v90, v90, v91
	s_nop 1
	v_add_f32_dpp v90, v90, v90 quad_perm:[1,0,3,2] row_mask:0xf bank_mask:0xf bound_ctrl:1
	s_nop 1
	v_add_f32_dpp v90, v90, v90 quad_perm:[2,3,0,1] row_mask:0xf bank_mask:0xf bound_ctrl:1
	s_nop 1
	v_add_f32_dpp v90, v90, v90 row_half_mirror row_mask:0xf bank_mask:0xf bound_ctrl:1
	ds_write_b32 v115, v90
	s_waitcnt lgkmcnt(0)
	s_barrier
	s_add_i32 s4, s4, 1
	s_cmpk_eq_i32 s4, 0x100
	s_cbranch_scc0 .Lrw_chunk
	s_setprio 0
	v_mov_b64_e32 v[32:33], v[16:17]
	v_mov_b64_e32 v[30:31], v[14:15]
	v_mov_b64_e32 v[28:29], v[12:13]
	v_mov_b64_e32 v[26:27], v[10:11]
	v_mov_b64_e32 v[24:25], v[8:9]
	v_mov_b64_e32 v[22:23], v[6:7]
	v_mov_b64_e32 v[20:21], v[4:5]
	v_mov_b64_e32 v[18:19], v[2:3]
	s_branch .LBB0_1293
